# stack12 + nt streaming hint on the adaLN GEMV read-once w_ada row loads (32 load sites in P0)
# speedup vs baseline: 1.0112x; 1.0071x over previous
.LBB8_12:
	s_mul_hi_i32 s0, s29, 0x2aaaaaab
	s_lshr_b32 s1, s0, 31
	s_ashr_i32 s0, s0, 4
	s_add_i32 s0, s0, s1
	s_lshl_b32 s1, s0, 9
	v_or_b32_e32 v2, s1, v0
	v_ashrrev_i32_e32 v3, 31, v2
	v_lshl_add_u64 v[2:3], v[2:3], 2, s[54:55]
	v_add_co_u32_e32 v4, vcc, 0x4000, v2
	s_mulk_i32 s0, 0x60
	s_nop 0
	v_addc_co_u32_e32 v5, vcc, 0, v3, vcc
	v_add_co_u32_e32 v6, vcc, s8, v2
	s_sub_i32 s0, s29, s0
	s_nop 0
	v_addc_co_u32_e32 v7, vcc, 0, v3, vcc
	global_load_dword v14, v[2:3], off
	global_load_dword v15, v[4:5], off
	global_load_dword v16, v[6:7], off
	v_add_co_u32_e32 v2, vcc, s9, v2
	s_lshl_b32 s0, s0, 8
	s_nop 0
	v_addc_co_u32_e32 v3, vcc, 0, v3, vcc
	global_load_dword v17, v[2:3], off
	v_or_b32_e32 v18, s0, v67
	v_ashrrev_i32_e32 v19, 31, v18
	v_or_b32_e32 v24, s1, v68
	v_lshlrev_b64 v[18:19], 2, v[18:19]
	v_mad_i64_i32 v[18:19], s[70:71], v24, s10, v[18:19]
	s_mov_b64 s[4:5], 0
	v_mov_b32_e32 v54, v74
	v_mov_b32_e32 v10, v55
	v_mov_b32_e32 v11, v55
	v_mov_b32_e32 v12, v55
	v_mov_b32_e32 v13, v55
	v_mov_b32_e32 v6, v55
	v_mov_b32_e32 v7, v55
	v_mov_b32_e32 v8, v55
	v_mov_b32_e32 v9, v55
	v_mov_b32_e32 v2, v55
	v_mov_b32_e32 v3, v55
	v_mov_b32_e32 v4, v55
	v_mov_b32_e32 v5, v55
	v_mov_b32_e32 v60, v55
	v_mov_b32_e32 v61, v55
	v_mov_b32_e32 v62, v55
	v_lshl_add_u64 v[58:59], s[56:57], 0, v[18:19]
	v_lshl_add_u64 v[64:65], v[58:59], 0, s[4:5]
	v_add_co_u32_e32 v106, vcc, s10, v64
	s_nop 1
	v_addc_co_u32_e32 v107, vcc, 0, v65, vcc
	v_add_co_u32_e32 v110, vcc, s11, v64
	s_nop 1
	global_load_dwordx4 v[102:105], v[64:65], off nt
	s_nop 0
	v_addc_co_u32_e32 v111, vcc, 0, v65, vcc
	v_add_co_u32_e32 v114, vcc, s12, v64
	s_nop 1
	v_addc_co_u32_e32 v115, vcc, 0, v65, vcc
	v_add_co_u32_e32 v118, vcc, s13, v64
	s_nop 1
	v_addc_co_u32_e32 v119, vcc, 0, v65, vcc
	v_add_co_u32_e32 v122, vcc, s14, v64
	s_nop 1
	v_addc_co_u32_e32 v123, vcc, 0, v65, vcc
	v_add_co_u32_e32 v126, vcc, s15, v64
	s_nop 1
	v_addc_co_u32_e32 v127, vcc, 0, v65, vcc
	v_add_co_u32_e32 v130, vcc, s16, v64
	s_nop 1
	v_addc_co_u32_e32 v131, vcc, 0, v65, vcc
	v_add_co_u32_e32 v134, vcc, s17, v64
	s_nop 1
	v_addc_co_u32_e32 v135, vcc, 0, v65, vcc
	v_add_co_u32_e32 v138, vcc, s20, v64
	s_nop 1
	v_addc_co_u32_e32 v139, vcc, 0, v65, vcc
	v_add_co_u32_e32 v142, vcc, s21, v64
	s_nop 1
	v_addc_co_u32_e32 v143, vcc, 0, v65, vcc
	v_add_co_u32_e32 v146, vcc, s22, v64
	s_nop 1
	v_addc_co_u32_e32 v147, vcc, 0, v65, vcc
	v_add_co_u32_e32 v150, vcc, s23, v64
	s_nop 1
	v_addc_co_u32_e32 v151, vcc, 0, v65, vcc
	v_add_co_u32_e32 v154, vcc, s24, v64
	s_nop 1
	v_addc_co_u32_e32 v155, vcc, 0, v65, vcc
	v_add_co_u32_e32 v158, vcc, s25, v64
	s_nop 1
	v_addc_co_u32_e32 v159, vcc, 0, v65, vcc
	v_add_co_u32_e32 v64, vcc, s28, v64
	s_nop 1
	v_addc_co_u32_e32 v65, vcc, 0, v65, vcc
	global_load_dwordx4 v[106:109], v[106:107], off nt
	s_nop 0
	global_load_dwordx4 v[110:113], v[110:111], off nt
	s_nop 0
	global_load_dwordx4 v[114:117], v[114:115], off nt
	s_nop 0
	global_load_dwordx4 v[118:121], v[118:119], off nt
	s_nop 0
	global_load_dwordx4 v[122:125], v[122:123], off nt
	s_nop 0
	global_load_dwordx4 v[126:129], v[126:127], off nt
	s_nop 0
	global_load_dwordx4 v[130:133], v[130:131], off nt
	s_nop 0
	global_load_dwordx4 v[134:137], v[134:135], off nt
	s_nop 0
	global_load_dwordx4 v[138:141], v[138:139], off nt
	s_nop 0
	global_load_dwordx4 v[142:145], v[142:143], off nt
	s_nop 0
	global_load_dwordx4 v[146:149], v[146:147], off nt
	s_nop 0
	global_load_dwordx4 v[150:153], v[150:151], off nt
	s_nop 0
	global_load_dwordx4 v[154:157], v[154:155], off nt
	s_nop 0
	global_load_dwordx4 v[158:161], v[158:159], off nt
	s_nop 0
	global_load_dwordx4 v[162:165], v[64:65], off nt
	v_mov_b32_e32 v63, v55
	s_waitcnt vmcnt(19)
	v_mul_f32_e32 v20, 0xbfb8aa3b, v14
	s_waitcnt vmcnt(18)
	v_mul_f32_e32 v21, 0xbfb8aa3b, v15
	s_waitcnt vmcnt(17)
	v_mul_f32_e32 v22, 0xbfb8aa3b, v16
	v_exp_f32_e32 v20, v20
	v_exp_f32_e32 v21, v21
	v_exp_f32_e32 v22, v22
	v_add_f32_e32 v20, 1.0, v20
	s_waitcnt vmcnt(16)
	v_mul_f32_e32 v23, 0xbfb8aa3b, v17
	v_exp_f32_e32 v23, v23
	v_add_f32_e32 v21, 1.0, v21
	v_add_f32_e32 v22, 1.0, v22
	v_rcp_f32_e32 v20, v20
	v_add_f32_e32 v23, 1.0, v23
	v_rcp_f32_e32 v21, v21
	v_rcp_f32_e32 v22, v22
	v_rcp_f32_e32 v23, v23
	v_pk_mul_f32 v[14:15], v[14:15], v[20:21]
	v_pk_mul_f32 v[16:17], v[16:17], v[22:23]
	ds_write_b128 v66, v[14:17] offset:32768
	s_waitcnt lgkmcnt(0)
	s_barrier
.LBB8_13:
.Lq_p0_loop:
	s_add_u32 s4, s4, 0x180000
	s_addc_u32 s5, s5, 0
	v_lshl_add_u64 v[196:197], v[58:59], 0, s[4:5]
	ds_read_b128 v[26:29], v54
	ds_read_b128 v[22:25], v54 offset:16
	ds_read_b128 v[18:21], v54 offset:32
	ds_read_b128 v[14:17], v54 offset:48
	ds_read_b128 v[30:33], v54 offset:64
	ds_read_b128 v[34:37], v54 offset:80
	ds_read_b128 v[38:41], v54 offset:96
	ds_read_b128 v[42:45], v54 offset:112
	ds_read_b128 v[46:49], v54 offset:128
	ds_read_b128 v[50:53], v54 offset:144
	ds_read_b128 v[78:81], v54 offset:160
	ds_read_b128 v[82:85], v54 offset:176
	ds_read_b128 v[86:89], v54 offset:192
	ds_read_b128 v[90:93], v54 offset:208
	ds_read_b128 v[94:97], v54 offset:224
	ds_read_b128 v[98:101], v54 offset:240
	s_waitcnt lgkmcnt(0)
	v_mov_b32_e32 v166, v25
	v_mov_b32_e32 v168, v21
	v_mov_b32_e32 v170, v17
	v_mov_b32_e32 v172, v33
	v_mov_b32_e32 v174, v37
	v_mov_b32_e32 v176, v41
	v_mov_b32_e32 v178, v45
	v_mov_b32_e32 v180, v49
	v_mov_b32_e32 v182, v53
	v_mov_b32_e32 v184, v81
	v_mov_b32_e32 v186, v85
	v_mov_b32_e32 v188, v89
	v_mov_b32_e32 v190, v93
	v_mov_b32_e32 v64, v29
	v_mov_b32_e32 v192, v97
	v_mov_b32_e32 v194, v101
	v_add_u32_e32 v54, 0x100, v54
	s_waitcnt vmcnt(15)
	v_pk_fma_f32 v[10:11], v[102:103], v[26:27], v[10:11] op_sel_hi:[1,0,1]
	v_pk_fma_f32 v[12:13], v[104:105], v[26:27], v[12:13] op_sel_hi:[1,0,1]
	v_pk_fma_f32 v[6:7], v[102:103], v[26:27], v[6:7] op_sel:[0,1,0]
	v_pk_fma_f32 v[8:9], v[104:105], v[26:27], v[8:9] op_sel:[0,1,0]
	v_pk_fma_f32 v[2:3], v[102:103], v[28:29], v[2:3] op_sel_hi:[1,0,1]
	v_pk_fma_f32 v[4:5], v[104:105], v[28:29], v[4:5] op_sel_hi:[1,0,1]
	v_pk_fma_f32 v[26:27], v[102:103], v[64:65], v[62:63] op_sel_hi:[1,0,1]
	v_pk_fma_f32 v[28:29], v[104:105], v[64:65], v[60:61] op_sel_hi:[1,0,1]
	global_load_dwordx4 v[102:105], v[196:197], off nt
	v_add_co_u32_e32 v198, vcc, s10, v196
	s_waitcnt vmcnt(15)
	v_pk_fma_f32 v[10:11], v[106:107], v[22:23], v[10:11] op_sel_hi:[1,0,1]
	v_pk_fma_f32 v[12:13], v[108:109], v[22:23], v[12:13] op_sel_hi:[1,0,1]
	v_pk_fma_f32 v[6:7], v[106:107], v[22:23], v[6:7] op_sel:[0,1,0]
	v_pk_fma_f32 v[8:9], v[108:109], v[22:23], v[8:9] op_sel:[0,1,0]
	v_pk_fma_f32 v[2:3], v[106:107], v[24:25], v[2:3] op_sel_hi:[1,0,1]
	v_pk_fma_f32 v[4:5], v[108:109], v[24:25], v[4:5] op_sel_hi:[1,0,1]
	v_pk_fma_f32 v[22:23], v[106:107], v[166:167], v[26:27] op_sel_hi:[1,0,1]
	v_pk_fma_f32 v[24:25], v[108:109], v[166:167], v[28:29] op_sel_hi:[1,0,1]
	v_addc_co_u32_e32 v199, vcc, 0, v197, vcc
	global_load_dwordx4 v[106:109], v[198:199], off nt
	v_add_co_u32_e32 v198, vcc, s11, v196
	s_waitcnt vmcnt(15)
	v_pk_fma_f32 v[10:11], v[110:111], v[18:19], v[10:11] op_sel_hi:[1,0,1]
	v_pk_fma_f32 v[12:13], v[112:113], v[18:19], v[12:13] op_sel_hi:[1,0,1]
	v_pk_fma_f32 v[6:7], v[110:111], v[18:19], v[6:7] op_sel:[0,1,0]
	v_pk_fma_f32 v[8:9], v[112:113], v[18:19], v[8:9] op_sel:[0,1,0]
	v_pk_fma_f32 v[2:3], v[110:111], v[20:21], v[2:3] op_sel_hi:[1,0,1]
	v_pk_fma_f32 v[4:5], v[112:113], v[20:21], v[4:5] op_sel_hi:[1,0,1]
	v_pk_fma_f32 v[18:19], v[110:111], v[168:169], v[22:23] op_sel_hi:[1,0,1]
	v_pk_fma_f32 v[20:21], v[112:113], v[168:169], v[24:25] op_sel_hi:[1,0,1]
	v_addc_co_u32_e32 v199, vcc, 0, v197, vcc
	global_load_dwordx4 v[110:113], v[198:199], off nt
	v_add_co_u32_e32 v198, vcc, s12, v196
	s_waitcnt vmcnt(15)
	v_pk_fma_f32 v[10:11], v[114:115], v[14:15], v[10:11] op_sel_hi:[1,0,1]
	v_pk_fma_f32 v[12:13], v[116:117], v[14:15], v[12:13] op_sel_hi:[1,0,1]
	v_pk_fma_f32 v[6:7], v[114:115], v[14:15], v[6:7] op_sel:[0,1,0]
	v_pk_fma_f32 v[8:9], v[116:117], v[14:15], v[8:9] op_sel:[0,1,0]
	v_pk_fma_f32 v[2:3], v[114:115], v[16:17], v[2:3] op_sel_hi:[1,0,1]
	v_pk_fma_f32 v[4:5], v[116:117], v[16:17], v[4:5] op_sel_hi:[1,0,1]
	v_pk_fma_f32 v[14:15], v[114:115], v[170:171], v[18:19] op_sel_hi:[1,0,1]
	v_pk_fma_f32 v[16:17], v[116:117], v[170:171], v[20:21] op_sel_hi:[1,0,1]
	v_addc_co_u32_e32 v199, vcc, 0, v197, vcc
	global_load_dwordx4 v[114:117], v[198:199], off nt
	v_add_co_u32_e32 v198, vcc, s13, v196
	s_waitcnt vmcnt(15)
	v_pk_fma_f32 v[10:11], v[118:119], v[30:31], v[10:11] op_sel_hi:[1,0,1]
	v_pk_fma_f32 v[12:13], v[120:121], v[30:31], v[12:13] op_sel_hi:[1,0,1]
	v_pk_fma_f32 v[6:7], v[118:119], v[30:31], v[6:7] op_sel:[0,1,0]
	v_pk_fma_f32 v[8:9], v[120:121], v[30:31], v[8:9] op_sel:[0,1,0]
	v_pk_fma_f32 v[2:3], v[118:119], v[32:33], v[2:3] op_sel_hi:[1,0,1]
	v_pk_fma_f32 v[4:5], v[120:121], v[32:33], v[4:5] op_sel_hi:[1,0,1]
	v_pk_fma_f32 v[14:15], v[118:119], v[172:173], v[14:15] op_sel_hi:[1,0,1]
	v_pk_fma_f32 v[16:17], v[120:121], v[172:173], v[16:17] op_sel_hi:[1,0,1]
	v_addc_co_u32_e32 v199, vcc, 0, v197, vcc
	global_load_dwordx4 v[118:121], v[198:199], off nt
	v_add_co_u32_e32 v198, vcc, s14, v196
	s_waitcnt vmcnt(15)
	v_pk_fma_f32 v[10:11], v[122:123], v[34:35], v[10:11] op_sel_hi:[1,0,1]
	v_pk_fma_f32 v[12:13], v[124:125], v[34:35], v[12:13] op_sel_hi:[1,0,1]
	v_pk_fma_f32 v[6:7], v[122:123], v[34:35], v[6:7] op_sel:[0,1,0]
	v_pk_fma_f32 v[8:9], v[124:125], v[34:35], v[8:9] op_sel:[0,1,0]
	v_pk_fma_f32 v[2:3], v[122:123], v[36:37], v[2:3] op_sel_hi:[1,0,1]
	v_pk_fma_f32 v[4:5], v[124:125], v[36:37], v[4:5] op_sel_hi:[1,0,1]
	v_pk_fma_f32 v[14:15], v[122:123], v[174:175], v[14:15] op_sel_hi:[1,0,1]
	v_pk_fma_f32 v[16:17], v[124:125], v[174:175], v[16:17] op_sel_hi:[1,0,1]
	v_addc_co_u32_e32 v199, vcc, 0, v197, vcc
	global_load_dwordx4 v[122:125], v[198:199], off nt
	v_add_co_u32_e32 v198, vcc, s15, v196
	s_waitcnt vmcnt(15)
	v_pk_fma_f32 v[10:11], v[126:127], v[38:39], v[10:11] op_sel_hi:[1,0,1]
	v_pk_fma_f32 v[12:13], v[128:129], v[38:39], v[12:13] op_sel_hi:[1,0,1]
	v_pk_fma_f32 v[6:7], v[126:127], v[38:39], v[6:7] op_sel:[0,1,0]
	v_pk_fma_f32 v[8:9], v[128:129], v[38:39], v[8:9] op_sel:[0,1,0]
	v_pk_fma_f32 v[2:3], v[126:127], v[40:41], v[2:3] op_sel_hi:[1,0,1]
	v_pk_fma_f32 v[4:5], v[128:129], v[40:41], v[4:5] op_sel_hi:[1,0,1]
	v_pk_fma_f32 v[14:15], v[126:127], v[176:177], v[14:15] op_sel_hi:[1,0,1]
	v_pk_fma_f32 v[16:17], v[128:129], v[176:177], v[16:17] op_sel_hi:[1,0,1]
	v_addc_co_u32_e32 v199, vcc, 0, v197, vcc
	global_load_dwordx4 v[126:129], v[198:199], off nt
	v_add_co_u32_e32 v198, vcc, s16, v196
	s_waitcnt vmcnt(15)
	v_pk_fma_f32 v[10:11], v[130:131], v[42:43], v[10:11] op_sel_hi:[1,0,1]
	v_pk_fma_f32 v[12:13], v[132:133], v[42:43], v[12:13] op_sel_hi:[1,0,1]
	v_pk_fma_f32 v[6:7], v[130:131], v[42:43], v[6:7] op_sel:[0,1,0]
	v_pk_fma_f32 v[8:9], v[132:133], v[42:43], v[8:9] op_sel:[0,1,0]
	v_pk_fma_f32 v[2:3], v[130:131], v[44:45], v[2:3] op_sel_hi:[1,0,1]
	v_pk_fma_f32 v[4:5], v[132:133], v[44:45], v[4:5] op_sel_hi:[1,0,1]
	v_pk_fma_f32 v[14:15], v[130:131], v[178:179], v[14:15] op_sel_hi:[1,0,1]
	v_pk_fma_f32 v[16:17], v[132:133], v[178:179], v[16:17] op_sel_hi:[1,0,1]
	v_addc_co_u32_e32 v199, vcc, 0, v197, vcc
	global_load_dwordx4 v[130:133], v[198:199], off nt
	v_add_co_u32_e32 v198, vcc, s17, v196
	s_waitcnt vmcnt(15)
	v_pk_fma_f32 v[10:11], v[134:135], v[46:47], v[10:11] op_sel_hi:[1,0,1]
	v_pk_fma_f32 v[12:13], v[136:137], v[46:47], v[12:13] op_sel_hi:[1,0,1]
	v_pk_fma_f32 v[6:7], v[134:135], v[46:47], v[6:7] op_sel:[0,1,0]
	v_pk_fma_f32 v[8:9], v[136:137], v[46:47], v[8:9] op_sel:[0,1,0]
	v_pk_fma_f32 v[2:3], v[134:135], v[48:49], v[2:3] op_sel_hi:[1,0,1]
	v_pk_fma_f32 v[4:5], v[136:137], v[48:49], v[4:5] op_sel_hi:[1,0,1]
	v_pk_fma_f32 v[14:15], v[134:135], v[180:181], v[14:15] op_sel_hi:[1,0,1]
	v_pk_fma_f32 v[16:17], v[136:137], v[180:181], v[16:17] op_sel_hi:[1,0,1]
	v_addc_co_u32_e32 v199, vcc, 0, v197, vcc
	global_load_dwordx4 v[134:137], v[198:199], off nt
	v_add_co_u32_e32 v198, vcc, s20, v196
	s_waitcnt vmcnt(15)
	v_pk_fma_f32 v[10:11], v[138:139], v[50:51], v[10:11] op_sel_hi:[1,0,1]
	v_pk_fma_f32 v[12:13], v[140:141], v[50:51], v[12:13] op_sel_hi:[1,0,1]
	v_pk_fma_f32 v[6:7], v[138:139], v[50:51], v[6:7] op_sel:[0,1,0]
	v_pk_fma_f32 v[8:9], v[140:141], v[50:51], v[8:9] op_sel:[0,1,0]
	v_pk_fma_f32 v[2:3], v[138:139], v[52:53], v[2:3] op_sel_hi:[1,0,1]
	v_pk_fma_f32 v[4:5], v[140:141], v[52:53], v[4:5] op_sel_hi:[1,0,1]
	v_pk_fma_f32 v[14:15], v[138:139], v[182:183], v[14:15] op_sel_hi:[1,0,1]
	v_pk_fma_f32 v[16:17], v[140:141], v[182:183], v[16:17] op_sel_hi:[1,0,1]
	v_addc_co_u32_e32 v199, vcc, 0, v197, vcc
	global_load_dwordx4 v[138:141], v[198:199], off nt
	v_add_co_u32_e32 v198, vcc, s21, v196
	s_waitcnt vmcnt(15)
	v_pk_fma_f32 v[10:11], v[142:143], v[78:79], v[10:11] op_sel_hi:[1,0,1]
	v_pk_fma_f32 v[12:13], v[144:145], v[78:79], v[12:13] op_sel_hi:[1,0,1]
	v_pk_fma_f32 v[6:7], v[142:143], v[78:79], v[6:7] op_sel:[0,1,0]
	v_pk_fma_f32 v[8:9], v[144:145], v[78:79], v[8:9] op_sel:[0,1,0]
	v_pk_fma_f32 v[2:3], v[142:143], v[80:81], v[2:3] op_sel_hi:[1,0,1]
	v_pk_fma_f32 v[4:5], v[144:145], v[80:81], v[4:5] op_sel_hi:[1,0,1]
	v_pk_fma_f32 v[14:15], v[142:143], v[184:185], v[14:15] op_sel_hi:[1,0,1]
	v_pk_fma_f32 v[16:17], v[144:145], v[184:185], v[16:17] op_sel_hi:[1,0,1]
	v_addc_co_u32_e32 v199, vcc, 0, v197, vcc
	global_load_dwordx4 v[142:145], v[198:199], off nt
	v_add_co_u32_e32 v198, vcc, s22, v196
	s_waitcnt vmcnt(15)
	v_pk_fma_f32 v[10:11], v[146:147], v[82:83], v[10:11] op_sel_hi:[1,0,1]
	v_pk_fma_f32 v[12:13], v[148:149], v[82:83], v[12:13] op_sel_hi:[1,0,1]
	v_pk_fma_f32 v[6:7], v[146:147], v[82:83], v[6:7] op_sel:[0,1,0]
	v_pk_fma_f32 v[8:9], v[148:149], v[82:83], v[8:9] op_sel:[0,1,0]
	v_pk_fma_f32 v[2:3], v[146:147], v[84:85], v[2:3] op_sel_hi:[1,0,1]
	v_pk_fma_f32 v[4:5], v[148:149], v[84:85], v[4:5] op_sel_hi:[1,0,1]
	v_pk_fma_f32 v[14:15], v[146:147], v[186:187], v[14:15] op_sel_hi:[1,0,1]
	v_pk_fma_f32 v[16:17], v[148:149], v[186:187], v[16:17] op_sel_hi:[1,0,1]
	v_addc_co_u32_e32 v199, vcc, 0, v197, vcc
	global_load_dwordx4 v[146:149], v[198:199], off nt
	v_add_co_u32_e32 v198, vcc, s23, v196
	s_waitcnt vmcnt(15)
	v_pk_fma_f32 v[10:11], v[150:151], v[86:87], v[10:11] op_sel_hi:[1,0,1]
	v_pk_fma_f32 v[12:13], v[152:153], v[86:87], v[12:13] op_sel_hi:[1,0,1]
	v_pk_fma_f32 v[6:7], v[150:151], v[86:87], v[6:7] op_sel:[0,1,0]
	v_pk_fma_f32 v[8:9], v[152:153], v[86:87], v[8:9] op_sel:[0,1,0]
	v_pk_fma_f32 v[2:3], v[150:151], v[88:89], v[2:3] op_sel_hi:[1,0,1]
	v_pk_fma_f32 v[4:5], v[152:153], v[88:89], v[4:5] op_sel_hi:[1,0,1]
	v_pk_fma_f32 v[14:15], v[150:151], v[188:189], v[14:15] op_sel_hi:[1,0,1]
	v_pk_fma_f32 v[16:17], v[152:153], v[188:189], v[16:17] op_sel_hi:[1,0,1]
	v_addc_co_u32_e32 v199, vcc, 0, v197, vcc
	global_load_dwordx4 v[150:153], v[198:199], off nt
	v_add_co_u32_e32 v198, vcc, s24, v196
	s_waitcnt vmcnt(15)
	v_pk_fma_f32 v[10:11], v[154:155], v[90:91], v[10:11] op_sel_hi:[1,0,1]
	v_pk_fma_f32 v[12:13], v[156:157], v[90:91], v[12:13] op_sel_hi:[1,0,1]
	v_pk_fma_f32 v[6:7], v[154:155], v[90:91], v[6:7] op_sel:[0,1,0]
	v_pk_fma_f32 v[8:9], v[156:157], v[90:91], v[8:9] op_sel:[0,1,0]
	v_pk_fma_f32 v[2:3], v[154:155], v[92:93], v[2:3] op_sel_hi:[1,0,1]
	v_pk_fma_f32 v[4:5], v[156:157], v[92:93], v[4:5] op_sel_hi:[1,0,1]
	v_pk_fma_f32 v[14:15], v[154:155], v[190:191], v[14:15] op_sel_hi:[1,0,1]
	v_pk_fma_f32 v[16:17], v[156:157], v[190:191], v[16:17] op_sel_hi:[1,0,1]
	v_addc_co_u32_e32 v199, vcc, 0, v197, vcc
	global_load_dwordx4 v[154:157], v[198:199], off nt
	v_add_co_u32_e32 v198, vcc, s25, v196
	s_waitcnt vmcnt(15)
	v_pk_fma_f32 v[10:11], v[158:159], v[94:95], v[10:11] op_sel_hi:[1,0,1]
	v_pk_fma_f32 v[12:13], v[160:161], v[94:95], v[12:13] op_sel_hi:[1,0,1]
	v_pk_fma_f32 v[6:7], v[158:159], v[94:95], v[6:7] op_sel:[0,1,0]
	v_pk_fma_f32 v[8:9], v[160:161], v[94:95], v[8:9] op_sel:[0,1,0]
	v_pk_fma_f32 v[2:3], v[158:159], v[96:97], v[2:3] op_sel_hi:[1,0,1]
	v_pk_fma_f32 v[4:5], v[160:161], v[96:97], v[4:5] op_sel_hi:[1,0,1]
	v_pk_fma_f32 v[14:15], v[158:159], v[192:193], v[14:15] op_sel_hi:[1,0,1]
	v_pk_fma_f32 v[16:17], v[160:161], v[192:193], v[16:17] op_sel_hi:[1,0,1]
	v_addc_co_u32_e32 v199, vcc, 0, v197, vcc
	global_load_dwordx4 v[158:161], v[198:199], off nt
	v_add_co_u32_e32 v198, vcc, s28, v196
	s_waitcnt vmcnt(15)
	v_pk_fma_f32 v[10:11], v[162:163], v[98:99], v[10:11] op_sel_hi:[1,0,1]
	v_pk_fma_f32 v[12:13], v[164:165], v[98:99], v[12:13] op_sel_hi:[1,0,1]
	v_pk_fma_f32 v[6:7], v[162:163], v[98:99], v[6:7] op_sel:[0,1,0]
	v_pk_fma_f32 v[8:9], v[164:165], v[98:99], v[8:9] op_sel:[0,1,0]
	v_pk_fma_f32 v[2:3], v[162:163], v[100:101], v[2:3] op_sel_hi:[1,0,1]
	v_pk_fma_f32 v[4:5], v[164:165], v[100:101], v[4:5] op_sel_hi:[1,0,1]
	v_pk_fma_f32 v[62:63], v[162:163], v[194:195], v[14:15] op_sel_hi:[1,0,1]
	v_pk_fma_f32 v[60:61], v[164:165], v[194:195], v[16:17] op_sel_hi:[1,0,1]
	v_addc_co_u32_e32 v199, vcc, 0, v197, vcc
	global_load_dwordx4 v[162:165], v[198:199], off nt
	s_cmp_eq_u32 s4, 0x480000
	s_cbranch_scc0 .Lq_p0_loop
	ds_read_b128 v[26:29], v54
	ds_read_b128 v[22:25], v54 offset:16
	ds_read_b128 v[18:21], v54 offset:32
	ds_read_b128 v[14:17], v54 offset:48
	ds_read_b128 v[30:33], v54 offset:64
	ds_read_b128 v[34:37], v54 offset:80
	ds_read_b128 v[38:41], v54 offset:96
	ds_read_b128 v[42:45], v54 offset:112
	ds_read_b128 v[46:49], v54 offset:128
	ds_read_b128 v[50:53], v54 offset:144
	ds_read_b128 v[78:81], v54 offset:160
	ds_read_b128 v[82:85], v54 offset:176
	ds_read_b128 v[86:89], v54 offset:192
	ds_read_b128 v[90:93], v54 offset:208
	ds_read_b128 v[94:97], v54 offset:224
	ds_read_b128 v[98:101], v54 offset:240
	s_waitcnt lgkmcnt(0)
	v_mov_b32_e32 v166, v25
	v_mov_b32_e32 v168, v21
	v_mov_b32_e32 v170, v17
	v_mov_b32_e32 v172, v33
	v_mov_b32_e32 v174, v37
	v_mov_b32_e32 v176, v41
	v_mov_b32_e32 v178, v45
	v_mov_b32_e32 v180, v49
	v_mov_b32_e32 v182, v53
	v_mov_b32_e32 v184, v81
	v_mov_b32_e32 v186, v85
	v_mov_b32_e32 v188, v89
	v_mov_b32_e32 v190, v93
	v_mov_b32_e32 v64, v29
	v_mov_b32_e32 v192, v97
	v_mov_b32_e32 v194, v101
	v_add_u32_e32 v54, 0x100, v54
	s_waitcnt vmcnt(15)
	v_pk_fma_f32 v[10:11], v[102:103], v[26:27], v[10:11] op_sel_hi:[1,0,1]
	v_pk_fma_f32 v[12:13], v[104:105], v[26:27], v[12:13] op_sel_hi:[1,0,1]
	v_pk_fma_f32 v[6:7], v[102:103], v[26:27], v[6:7] op_sel:[0,1,0]
	v_pk_fma_f32 v[8:9], v[104:105], v[26:27], v[8:9] op_sel:[0,1,0]
	v_pk_fma_f32 v[2:3], v[102:103], v[28:29], v[2:3] op_sel_hi:[1,0,1]
	v_pk_fma_f32 v[4:5], v[104:105], v[28:29], v[4:5] op_sel_hi:[1,0,1]
	v_pk_fma_f32 v[26:27], v[102:103], v[64:65], v[62:63] op_sel_hi:[1,0,1]
	v_pk_fma_f32 v[28:29], v[104:105], v[64:65], v[60:61] op_sel_hi:[1,0,1]
	s_waitcnt vmcnt(14)
	v_pk_fma_f32 v[10:11], v[106:107], v[22:23], v[10:11] op_sel_hi:[1,0,1]
	v_pk_fma_f32 v[12:13], v[108:109], v[22:23], v[12:13] op_sel_hi:[1,0,1]
	v_pk_fma_f32 v[6:7], v[106:107], v[22:23], v[6:7] op_sel:[0,1,0]
	v_pk_fma_f32 v[8:9], v[108:109], v[22:23], v[8:9] op_sel:[0,1,0]
	v_pk_fma_f32 v[2:3], v[106:107], v[24:25], v[2:3] op_sel_hi:[1,0,1]
	v_pk_fma_f32 v[4:5], v[108:109], v[24:25], v[4:5] op_sel_hi:[1,0,1]
	v_pk_fma_f32 v[22:23], v[106:107], v[166:167], v[26:27] op_sel_hi:[1,0,1]
	v_pk_fma_f32 v[24:25], v[108:109], v[166:167], v[28:29] op_sel_hi:[1,0,1]
	s_waitcnt vmcnt(13)
	v_pk_fma_f32 v[10:11], v[110:111], v[18:19], v[10:11] op_sel_hi:[1,0,1]
	v_pk_fma_f32 v[12:13], v[112:113], v[18:19], v[12:13] op_sel_hi:[1,0,1]
	v_pk_fma_f32 v[6:7], v[110:111], v[18:19], v[6:7] op_sel:[0,1,0]
	v_pk_fma_f32 v[8:9], v[112:113], v[18:19], v[8:9] op_sel:[0,1,0]
	v_pk_fma_f32 v[2:3], v[110:111], v[20:21], v[2:3] op_sel_hi:[1,0,1]
	v_pk_fma_f32 v[4:5], v[112:113], v[20:21], v[4:5] op_sel_hi:[1,0,1]
	v_pk_fma_f32 v[18:19], v[110:111], v[168:169], v[22:23] op_sel_hi:[1,0,1]
	v_pk_fma_f32 v[20:21], v[112:113], v[168:169], v[24:25] op_sel_hi:[1,0,1]
	s_waitcnt vmcnt(12)
	v_pk_fma_f32 v[10:11], v[114:115], v[14:15], v[10:11] op_sel_hi:[1,0,1]
	v_pk_fma_f32 v[12:13], v[116:117], v[14:15], v[12:13] op_sel_hi:[1,0,1]
	v_pk_fma_f32 v[6:7], v[114:115], v[14:15], v[6:7] op_sel:[0,1,0]
	v_pk_fma_f32 v[8:9], v[116:117], v[14:15], v[8:9] op_sel:[0,1,0]
	v_pk_fma_f32 v[2:3], v[114:115], v[16:17], v[2:3] op_sel_hi:[1,0,1]
	v_pk_fma_f32 v[4:5], v[116:117], v[16:17], v[4:5] op_sel_hi:[1,0,1]
	v_pk_fma_f32 v[14:15], v[114:115], v[170:171], v[18:19] op_sel_hi:[1,0,1]
	v_pk_fma_f32 v[16:17], v[116:117], v[170:171], v[20:21] op_sel_hi:[1,0,1]
	s_waitcnt vmcnt(11)
	v_pk_fma_f32 v[10:11], v[118:119], v[30:31], v[10:11] op_sel_hi:[1,0,1]
	v_pk_fma_f32 v[12:13], v[120:121], v[30:31], v[12:13] op_sel_hi:[1,0,1]
	v_pk_fma_f32 v[6:7], v[118:119], v[30:31], v[6:7] op_sel:[0,1,0]
	v_pk_fma_f32 v[8:9], v[120:121], v[30:31], v[8:9] op_sel:[0,1,0]
	v_pk_fma_f32 v[2:3], v[118:119], v[32:33], v[2:3] op_sel_hi:[1,0,1]
	v_pk_fma_f32 v[4:5], v[120:121], v[32:33], v[4:5] op_sel_hi:[1,0,1]
	v_pk_fma_f32 v[14:15], v[118:119], v[172:173], v[14:15] op_sel_hi:[1,0,1]
	v_pk_fma_f32 v[16:17], v[120:121], v[172:173], v[16:17] op_sel_hi:[1,0,1]
	s_waitcnt vmcnt(10)
	v_pk_fma_f32 v[10:11], v[122:123], v[34:35], v[10:11] op_sel_hi:[1,0,1]
	v_pk_fma_f32 v[12:13], v[124:125], v[34:35], v[12:13] op_sel_hi:[1,0,1]
	v_pk_fma_f32 v[6:7], v[122:123], v[34:35], v[6:7] op_sel:[0,1,0]
	v_pk_fma_f32 v[8:9], v[124:125], v[34:35], v[8:9] op_sel:[0,1,0]
	v_pk_fma_f32 v[2:3], v[122:123], v[36:37], v[2:3] op_sel_hi:[1,0,1]
	v_pk_fma_f32 v[4:5], v[124:125], v[36:37], v[4:5] op_sel_hi:[1,0,1]
	v_pk_fma_f32 v[14:15], v[122:123], v[174:175], v[14:15] op_sel_hi:[1,0,1]
	v_pk_fma_f32 v[16:17], v[124:125], v[174:175], v[16:17] op_sel_hi:[1,0,1]
	s_waitcnt vmcnt(9)
	v_pk_fma_f32 v[10:11], v[126:127], v[38:39], v[10:11] op_sel_hi:[1,0,1]
	v_pk_fma_f32 v[12:13], v[128:129], v[38:39], v[12:13] op_sel_hi:[1,0,1]
	v_pk_fma_f32 v[6:7], v[126:127], v[38:39], v[6:7] op_sel:[0,1,0]
	v_pk_fma_f32 v[8:9], v[128:129], v[38:39], v[8:9] op_sel:[0,1,0]
	v_pk_fma_f32 v[2:3], v[126:127], v[40:41], v[2:3] op_sel_hi:[1,0,1]
	v_pk_fma_f32 v[4:5], v[128:129], v[40:41], v[4:5] op_sel_hi:[1,0,1]
	v_pk_fma_f32 v[14:15], v[126:127], v[176:177], v[14:15] op_sel_hi:[1,0,1]
	v_pk_fma_f32 v[16:17], v[128:129], v[176:177], v[16:17] op_sel_hi:[1,0,1]
	s_waitcnt vmcnt(8)
	v_pk_fma_f32 v[10:11], v[130:131], v[42:43], v[10:11] op_sel_hi:[1,0,1]
	v_pk_fma_f32 v[12:13], v[132:133], v[42:43], v[12:13] op_sel_hi:[1,0,1]
	v_pk_fma_f32 v[6:7], v[130:131], v[42:43], v[6:7] op_sel:[0,1,0]
	v_pk_fma_f32 v[8:9], v[132:133], v[42:43], v[8:9] op_sel:[0,1,0]
	v_pk_fma_f32 v[2:3], v[130:131], v[44:45], v[2:3] op_sel_hi:[1,0,1]
	v_pk_fma_f32 v[4:5], v[132:133], v[44:45], v[4:5] op_sel_hi:[1,0,1]
	v_pk_fma_f32 v[14:15], v[130:131], v[178:179], v[14:15] op_sel_hi:[1,0,1]
	v_pk_fma_f32 v[16:17], v[132:133], v[178:179], v[16:17] op_sel_hi:[1,0,1]
	s_waitcnt vmcnt(7)
	v_pk_fma_f32 v[10:11], v[134:135], v[46:47], v[10:11] op_sel_hi:[1,0,1]
	v_pk_fma_f32 v[12:13], v[136:137], v[46:47], v[12:13] op_sel_hi:[1,0,1]
	v_pk_fma_f32 v[6:7], v[134:135], v[46:47], v[6:7] op_sel:[0,1,0]
	v_pk_fma_f32 v[8:9], v[136:137], v[46:47], v[8:9] op_sel:[0,1,0]
	v_pk_fma_f32 v[2:3], v[134:135], v[48:49], v[2:3] op_sel_hi:[1,0,1]
	v_pk_fma_f32 v[4:5], v[136:137], v[48:49], v[4:5] op_sel_hi:[1,0,1]
	v_pk_fma_f32 v[14:15], v[134:135], v[180:181], v[14:15] op_sel_hi:[1,0,1]
	v_pk_fma_f32 v[16:17], v[136:137], v[180:181], v[16:17] op_sel_hi:[1,0,1]
	s_waitcnt vmcnt(6)
	v_pk_fma_f32 v[10:11], v[138:139], v[50:51], v[10:11] op_sel_hi:[1,0,1]
	v_pk_fma_f32 v[12:13], v[140:141], v[50:51], v[12:13] op_sel_hi:[1,0,1]
	v_pk_fma_f32 v[6:7], v[138:139], v[50:51], v[6:7] op_sel:[0,1,0]
	v_pk_fma_f32 v[8:9], v[140:141], v[50:51], v[8:9] op_sel:[0,1,0]
	v_pk_fma_f32 v[2:3], v[138:139], v[52:53], v[2:3] op_sel_hi:[1,0,1]
	v_pk_fma_f32 v[4:5], v[140:141], v[52:53], v[4:5] op_sel_hi:[1,0,1]
	v_pk_fma_f32 v[14:15], v[138:139], v[182:183], v[14:15] op_sel_hi:[1,0,1]
	v_pk_fma_f32 v[16:17], v[140:141], v[182:183], v[16:17] op_sel_hi:[1,0,1]
	s_waitcnt vmcnt(5)
	v_pk_fma_f32 v[10:11], v[142:143], v[78:79], v[10:11] op_sel_hi:[1,0,1]
	v_pk_fma_f32 v[12:13], v[144:145], v[78:79], v[12:13] op_sel_hi:[1,0,1]
	v_pk_fma_f32 v[6:7], v[142:143], v[78:79], v[6:7] op_sel:[0,1,0]
	v_pk_fma_f32 v[8:9], v[144:145], v[78:79], v[8:9] op_sel:[0,1,0]
	v_pk_fma_f32 v[2:3], v[142:143], v[80:81], v[2:3] op_sel_hi:[1,0,1]
	v_pk_fma_f32 v[4:5], v[144:145], v[80:81], v[4:5] op_sel_hi:[1,0,1]
	v_pk_fma_f32 v[14:15], v[142:143], v[184:185], v[14:15] op_sel_hi:[1,0,1]
	v_pk_fma_f32 v[16:17], v[144:145], v[184:185], v[16:17] op_sel_hi:[1,0,1]
	s_waitcnt vmcnt(4)
	v_pk_fma_f32 v[10:11], v[146:147], v[82:83], v[10:11] op_sel_hi:[1,0,1]
	v_pk_fma_f32 v[12:13], v[148:149], v[82:83], v[12:13] op_sel_hi:[1,0,1]
	v_pk_fma_f32 v[6:7], v[146:147], v[82:83], v[6:7] op_sel:[0,1,0]
	v_pk_fma_f32 v[8:9], v[148:149], v[82:83], v[8:9] op_sel:[0,1,0]
	v_pk_fma_f32 v[2:3], v[146:147], v[84:85], v[2:3] op_sel_hi:[1,0,1]
	v_pk_fma_f32 v[4:5], v[148:149], v[84:85], v[4:5] op_sel_hi:[1,0,1]
	v_pk_fma_f32 v[14:15], v[146:147], v[186:187], v[14:15] op_sel_hi:[1,0,1]
	v_pk_fma_f32 v[16:17], v[148:149], v[186:187], v[16:17] op_sel_hi:[1,0,1]
	s_waitcnt vmcnt(3)
	v_pk_fma_f32 v[10:11], v[150:151], v[86:87], v[10:11] op_sel_hi:[1,0,1]
	v_pk_fma_f32 v[12:13], v[152:153], v[86:87], v[12:13] op_sel_hi:[1,0,1]
	v_pk_fma_f32 v[6:7], v[150:151], v[86:87], v[6:7] op_sel:[0,1,0]
	v_pk_fma_f32 v[8:9], v[152:153], v[86:87], v[8:9] op_sel:[0,1,0]
	v_pk_fma_f32 v[2:3], v[150:151], v[88:89], v[2:3] op_sel_hi:[1,0,1]
	v_pk_fma_f32 v[4:5], v[152:153], v[88:89], v[4:5] op_sel_hi:[1,0,1]
	v_pk_fma_f32 v[14:15], v[150:151], v[188:189], v[14:15] op_sel_hi:[1,0,1]
	v_pk_fma_f32 v[16:17], v[152:153], v[188:189], v[16:17] op_sel_hi:[1,0,1]
	s_waitcnt vmcnt(2)
	v_pk_fma_f32 v[10:11], v[154:155], v[90:91], v[10:11] op_sel_hi:[1,0,1]
	v_pk_fma_f32 v[12:13], v[156:157], v[90:91], v[12:13] op_sel_hi:[1,0,1]
	v_pk_fma_f32 v[6:7], v[154:155], v[90:91], v[6:7] op_sel:[0,1,0]
	v_pk_fma_f32 v[8:9], v[156:157], v[90:91], v[8:9] op_sel:[0,1,0]
	v_pk_fma_f32 v[2:3], v[154:155], v[92:93], v[2:3] op_sel_hi:[1,0,1]
	v_pk_fma_f32 v[4:5], v[156:157], v[92:93], v[4:5] op_sel_hi:[1,0,1]
	v_pk_fma_f32 v[14:15], v[154:155], v[190:191], v[14:15] op_sel_hi:[1,0,1]
	v_pk_fma_f32 v[16:17], v[156:157], v[190:191], v[16:17] op_sel_hi:[1,0,1]
	s_waitcnt vmcnt(1)
	v_pk_fma_f32 v[10:11], v[158:159], v[94:95], v[10:11] op_sel_hi:[1,0,1]
	v_pk_fma_f32 v[12:13], v[160:161], v[94:95], v[12:13] op_sel_hi:[1,0,1]
	v_pk_fma_f32 v[6:7], v[158:159], v[94:95], v[6:7] op_sel:[0,1,0]
	v_pk_fma_f32 v[8:9], v[160:161], v[94:95], v[8:9] op_sel:[0,1,0]
	v_pk_fma_f32 v[2:3], v[158:159], v[96:97], v[2:3] op_sel_hi:[1,0,1]
	v_pk_fma_f32 v[4:5], v[160:161], v[96:97], v[4:5] op_sel_hi:[1,0,1]
	v_pk_fma_f32 v[14:15], v[158:159], v[192:193], v[14:15] op_sel_hi:[1,0,1]
	v_pk_fma_f32 v[16:17], v[160:161], v[192:193], v[16:17] op_sel_hi:[1,0,1]
	s_waitcnt vmcnt(0)
	v_pk_fma_f32 v[10:11], v[162:163], v[98:99], v[10:11] op_sel_hi:[1,0,1]
	v_pk_fma_f32 v[12:13], v[164:165], v[98:99], v[12:13] op_sel_hi:[1,0,1]
	v_pk_fma_f32 v[6:7], v[162:163], v[98:99], v[6:7] op_sel:[0,1,0]
	v_pk_fma_f32 v[8:9], v[164:165], v[98:99], v[8:9] op_sel:[0,1,0]
	v_pk_fma_f32 v[2:3], v[162:163], v[100:101], v[2:3] op_sel_hi:[1,0,1]
	v_pk_fma_f32 v[4:5], v[164:165], v[100:101], v[4:5] op_sel_hi:[1,0,1]
	v_pk_fma_f32 v[62:63], v[162:163], v[194:195], v[14:15] op_sel_hi:[1,0,1]
	v_pk_fma_f32 v[60:61], v[164:165], v[194:195], v[16:17] op_sel_hi:[1,0,1]
	s_add_i32 s1, s29, 0x5f
	ds_write_b128 v69, v[10:13]
	ds_write_b128 v69, v[6:9] offset:1024
	ds_write_b128 v69, v[2:5] offset:2048
	ds_write_b32 v70, v62
	ds_write_b32 v71, v63
	ds_write_b32 v72, v60
	ds_write_b32 v73, v61
	s_cmpk_lt_u32 s1, 0xbf
	v_or_b32_sdwa v2, s0, v0 dst_sel:DWORD dst_unused:UNUSED_PAD src0_sel:DWORD src1_sel:BYTE_0
	s_cselect_b64 s[4:5], -1, 0
	s_ashr_i32 s1, s0, 31
	v_ashrrev_i32_e32 v3, 31, v2
	v_lshl_add_u64 v[2:3], v[2:3], 2, s[58:59]
	v_lshl_add_u64 v[4:5], s[0:1], 2, v[56:57]
	s_mov_b64 s[0:1], 0
	v_mov_b32_e32 v6, v77
	v_mov_b32_e32 v7, v76
	v_mov_b32_e32 v8, v75
	s_waitcnt lgkmcnt(0)
	s_barrier
	s_branch .LBB8_16
